# XCD-local grid syncs at sites 4,8,9,10,20 (XCD leader skips cross-XCD level when all consumers are on the producer XCD), guarded by a launch-time check that hardware XCC id == blockIdx%8 for every wor
# baseline (speedup 1.0000x reference)
; #define LAS __attribute__((address_space(3)))
; __device__ __forceinline__ unsigned xb_add(unsigned* p, unsigned v) { return __hip_atomic_fetch_add(p, v, __ATOMIC_RELAXED, __HIP_MEMORY_SCOPE_AGENT); }
; __device__ __forceinline__ unsigned xb_xcc_id() { return (unsigned)__builtin_amdgcn_s_getreg((3 << 11) | 20) & 0xFu; }
; #define KA_DEF const __attribute__((address_space(4))) KArgs* ka_ = (const __attribute__((address_space(4))) KArgs*)__builtin_amdgcn_kernarg_segment_ptr(); asm volatile("" : "+s"(ka_));
; __device__ __forceinline__ XcdBarrier xcd_barrier_post(unsigned* bar, volatile LAS unsigned* st) {
;     XcdBarrier b; b.bar = bar; b.x = xb_xcc_id(); b.st = st; b.tid = threadIdx.x;
;     if (threadIdx.x == 0) (void)xb_add(&bar[XB_XCNT(b.x)], 1u);
;     return b;
; }
; __global__ void __launch_bounds__(512, 2) mega_fwd(KArgs a) {
;     ...
;     volatile LAS unsigned* MISC = (volatile LAS unsigned*)(lds + 131072 + 320);
;     if (threadIdx.x < 32) MISC[threadIdx.x] = 0u;
;     __syncthreads();
;     { KA_DEF (void)xcd_barrier_post((unsigned*)WSP(WS_CTL), MISC + 8); }
_Z8mega_fwd5KArgs:
	s_load_dwordx2 s[90:91], s[0:1], 0x108
	s_load_dword s33, s[0:1], 0x110
	s_mov_b64 s[88:89], s[0:1]
	s_mov_b32 s86, s2
	s_add_u32 s2, s88, 0x108
	v_and_b32_e32 v1, 0x3ff, v0
	s_addc_u32 s3, s89, 0
	v_readfirstlane_b32 s5, v1
	v_cmp_gt_u32_e32 vcc, 32, v1
	s_and_saveexec_b64 s[0:1], vcc
	v_lshl_add_u32 v2, v1, 2, 0
	v_add_u32_e32 v2, 0x20140, v2
	v_mov_b32_e32 v3, 0
	ds_write_b32 v2, v3
	s_or_b64 exec, exec, s[0:1]
	s_mov_b64 s[6:7], s[88:89]
	s_waitcnt lgkmcnt(0)
	s_barrier
	s_getreg_b32 s10, hwreg(HW_REG_XCC_ID, 0, 4)
	s_mov_b32 s4, 0
	v_cmp_eq_u32_e32 vcc, 0, v1
	s_and_saveexec_b64 s[0:1], vcc
	s_cbranch_execz .LBB0_5
	s_mov_b64 s[8:9], exec
	v_mbcnt_lo_u32_b32 v2, s8, 0
	v_mbcnt_hi_u32_b32 v2, s9, v2
	v_cmp_eq_u32_e32 vcc, 0, v2
	s_and_b64 s[12:13], exec, vcc
	s_mov_b64 exec, s[12:13]
	s_cbranch_execz .LBB0_5
	s_load_dwordx2 s[6:7], s[6:7], 0x100
	s_lshl_b32 s10, s10, 8
	s_and_b32 s10, s10, 0xf00
	v_mov_b32_e32 v2, 0x17900000
	s_waitcnt lgkmcnt(0)
	s_lshl_b32 s11, s86, 8
	s_and_b32 s11, s11, 0x700
	s_cmp_eq_u32 s11, s10
	s_cbranch_scc1 .Lmy_xcc_ok
	v_mov_b32_e32 v3, 1
	v_mov_b32_e32 v4, 0x17903800
	global_atomic_add v4, v3, s[6:7]
.Lmy_xcc_ok:
	s_add_u32 s6, s6, s10
	s_addc_u32 s7, s7, 0
	s_bcnt1_i32_b64 s8, s[8:9]
	v_mov_b32_e32 v3, s8
	global_atomic_add v2, v3, s[6:7] offset:1024

; #define KA_DEF const __attribute__((address_space(4))) KArgs* ka_ = (const __attribute__((address_space(4))) KArgs*)__builtin_amdgcn_kernarg_segment_ptr(); asm volatile("" : "+s"(ka_));
; #define MEMSSQ ((float*)WSP(WS_MEMSSQ))
; __global__ void __launch_bounds__(512, 2) mega_fwd(KArgs a) {
;     ...
;     GSYNC();
;     { KA_DEF pg8::EpiBf16S E{KVRAW, 8192, MEMSSQ}; run_gemm(TIDX, lds, MEMB, XKV, NBATCH * MEMLEN, 8192, 1024, E); }
.LBB0_1621:
	s_or_b64 exec, exec, s[0:1]
	s_mov_b64 s[0:1], s[88:89]
	s_waitcnt lgkmcnt(0)
	s_barrier
	s_load_dwordx2 s[0:1], s[0:1], 0x100
	s_movk_i32 s4, 0x800
	s_movk_i32 s5, 0x2000
	s_movk_i32 s18, 0x400
	s_waitcnt lgkmcnt(0)
	v_mov_b32_e32 v1, 0x17903800
	global_load_dword v1, v1, s[0:1] sc1
	s_waitcnt vmcnt(0)
	v_readfirstlane_b32 s2, v1
	s_nop 0
	s_cmp_eq_u32 s2, 0
	s_cselect_b32 s2, 1, 0
	s_nop 0
	v_writelane_b32 v254, s2, 42
	s_add_u32 s2, s0, 0x8100000
	s_addc_u32 s3, s1, 0
	s_add_u32 s6, s0, 0x3000000
	s_addc_u32 s7, s1, 0
	s_ashr_i32 s8, s4, 31
	s_lshr_b32 s8, s8, 24
	s_add_i32 s4, s4, s8
	s_ashr_i32 s28, s4, 8
	s_ashr_i32 s4, s5, 31
	s_lshr_b32 s4, s4, 24
	s_add_i32 s5, s5, s4
	s_ashr_i32 s12, s5, 8
	s_mul_i32 s4, s12, s28
	v_mov_b32_e32 v12, v220
	s_cmp_ge_i32 s86, s4
	v_readfirstlane_b32 s20, v12
	s_cbranch_scc1 .LBB0_1650
	s_ashr_i32 s5, s4, 31
	s_lshr_b32 s8, s5, 29
	s_add_i32 s8, s4, s8
	s_ashr_i32 s29, s8, 3
	s_and_b32 s8, s8, -8
	s_ashr_i32 s31, s86, 31
	s_sub_i32 s30, s4, s8
	s_lshr_b32 s8, s31, 29
	s_add_i32 s10, s86, s8
	s_and_b32 s8, s10, -8
	s_sub_i32 s11, s86, s8
	s_add_i32 s34, s29, 1
	s_cmp_ge_i32 s11, s30
	s_mul_i32 s35, s34, s30
	s_cbranch_scc0 .LBB0_1624
	s_sub_i32 s8, s11, s30
	s_mul_i32 s8, s8, s29
	s_add_i32 s13, s8, s35
	s_cbranch_execz .LBB0_1625
	s_branch .LBB0_1626

; __device__ __forceinline__ unsigned xb_ld(unsigned* p)              { return __hip_atomic_load(p, __ATOMIC_RELAXED, __HIP_MEMORY_SCOPE_AGENT); }
; __device__ __forceinline__ unsigned xb_add(unsigned* p, unsigned v) { return __hip_atomic_fetch_add(p, v, __ATOMIC_RELAXED, __HIP_MEMORY_SCOPE_AGENT); }
; #define XB_SPIN(cond, bar) do { unsigned _sp = 0; while (cond) { __builtin_amdgcn_s_sleep(1); \
;     if ((++_sp & 255u) == 0u) { if (xb_ld(&(bar)[XB_TMO])) break; if (_sp > XB_SPIN_CAP) { atomicAdd(&(bar)[XB_TMO], 1u); break; } } } } while (0)
; __device__ __forceinline__ void xcd_barrier(const XcdBarrier& b) {
;     ...
;         if (old + 1u == (gen + 1u) * nloc) {
;             __builtin_amdgcn_fence(__ATOMIC_RELEASE, "agent");
;             asm volatile("s_waitcnt vmcnt(0)" ::: "memory");
;             const unsigned og = xb_add(&bar[XB_TOP], 1u);
;             const unsigned tg = og / nx;
;             if (og + 1u == (tg + 1u) * nx) xb_add(&bar[XB_TOPGEN], 1u);
;             else XB_SPIN(xb_ld(&bar[XB_TOPGEN]) == tg, bar);
;             __builtin_amdgcn_fence(__ATOMIC_ACQUIRE, "agent");
.LBB0_3204:
	s_andn2_saveexec_b64 s[10:11], s[10:11]
	s_cbranch_execz .LBB0_3224
	s_mov_b64 s[10:11], exec
	v_readlane_b32 vcc_lo, v254, 42
	s_nop 0
	s_cmp_eq_u32 vcc_lo, 0
	s_cbranch_scc1 .Lmy_gsync_4
	buffer_inv sc1
	s_branch .Lmy_lsync_4
.Lmy_gsync_4:
	buffer_wbl2 sc1
	s_waitcnt lgkmcnt(0)
	s_waitcnt vmcnt(0)
	buffer_inv sc1
	v_mbcnt_lo_u32_b32 v1, s10, 0
	v_mbcnt_hi_u32_b32 v1, s11, v1
	v_cmp_eq_u32_e32 vcc, 0, v1
	s_and_saveexec_b64 s[14:15], vcc
	s_cbranch_execz .LBB0_3207
	s_bcnt1_i32_b64 s10, s[10:11]
	v_mov_b32_e32 v3, s10
	v_mov_b32_e32 v4, 0x17903000
	global_atomic_add v3, v4, v3, s[4:5] offset:1024 sc0

; __device__ __forceinline__ unsigned xb_add(unsigned* p, unsigned v) { return __hip_atomic_fetch_add(p, v, __ATOMIC_RELAXED, __HIP_MEMORY_SCOPE_AGENT); }
; __device__ __forceinline__ void xcd_barrier(const XcdBarrier& b) {
;     ...
;             xb_add(&bar[XB_XGEN(b.x)], 1u);
;             asm volatile("s_waitcnt vmcnt(0)" ::: "memory");
.Lmy_lsync_4:
	s_mov_b64 s[4:5], exec
	v_mbcnt_lo_u32_b32 v1, s4, 0
	v_mbcnt_hi_u32_b32 v1, s5, v1
	v_cmp_eq_u32_e32 vcc, 0, v1
	s_waitcnt vmcnt(0)
	s_and_saveexec_b64 s[10:11], vcc
	s_cbranch_execz .LBB0_3223
	s_bcnt1_i32_b64 s4, s[4:5]
	v_mov_b32_e32 v1, s4
	global_atomic_add v241, v1, s[8:9] offset:1024

; __device__ __forceinline__ unsigned xb_ld(unsigned* p)              { return __hip_atomic_load(p, __ATOMIC_RELAXED, __HIP_MEMORY_SCOPE_AGENT); }
; __device__ __forceinline__ unsigned xb_add(unsigned* p, unsigned v) { return __hip_atomic_fetch_add(p, v, __ATOMIC_RELAXED, __HIP_MEMORY_SCOPE_AGENT); }
; #define XB_SPIN(cond, bar) do { unsigned _sp = 0; while (cond) { __builtin_amdgcn_s_sleep(1); \
;     if ((++_sp & 255u) == 0u) { if (xb_ld(&(bar)[XB_TMO])) break; if (_sp > XB_SPIN_CAP) { atomicAdd(&(bar)[XB_TMO], 1u); break; } } } } while (0)
; __device__ __forceinline__ void xcd_barrier(const XcdBarrier& b) {
;     ...
;         if (old + 1u == (gen + 1u) * nloc) {
;             __builtin_amdgcn_fence(__ATOMIC_RELEASE, "agent");
;             asm volatile("s_waitcnt vmcnt(0)" ::: "memory");
;             const unsigned og = xb_add(&bar[XB_TOP], 1u);
;             const unsigned tg = og / nx;
;             if (og + 1u == (tg + 1u) * nx) xb_add(&bar[XB_TOPGEN], 1u);
;             else XB_SPIN(xb_ld(&bar[XB_TOPGEN]) == tg, bar);
;             __builtin_amdgcn_fence(__ATOMIC_ACQUIRE, "agent");
.LBB0_3856:
	s_andn2_saveexec_b64 s[6:7], s[6:7]
	s_cbranch_execz .LBB0_3876
	s_mov_b64 s[6:7], exec
	v_readlane_b32 vcc_lo, v254, 42
	s_nop 0
	s_cmp_eq_u32 vcc_lo, 0
	s_cbranch_scc1 .Lmy_gsync_8
	buffer_inv sc1
	s_branch .Lmy_lsync_8
.Lmy_gsync_8:
	buffer_wbl2 sc1
	s_waitcnt lgkmcnt(0)
	s_waitcnt vmcnt(0)
	buffer_inv sc1
	v_mbcnt_lo_u32_b32 v1, s6, 0
	v_mbcnt_hi_u32_b32 v1, s7, v1
	v_cmp_eq_u32_e32 vcc, 0, v1
	s_and_saveexec_b64 s[8:9], vcc
	s_cbranch_execz .LBB0_3859
	s_bcnt1_i32_b64 s6, s[6:7]
	v_mov_b32_e32 v3, s6
	v_mov_b32_e32 v4, 0x17903000
	global_atomic_add v3, v4, v3, s[2:3] offset:1024 sc0

; __device__ __forceinline__ unsigned xb_add(unsigned* p, unsigned v) { return __hip_atomic_fetch_add(p, v, __ATOMIC_RELAXED, __HIP_MEMORY_SCOPE_AGENT); }
; __device__ __forceinline__ void xcd_barrier(const XcdBarrier& b) {
;     ...
;             xb_add(&bar[XB_XGEN(b.x)], 1u);
;             asm volatile("s_waitcnt vmcnt(0)" ::: "memory");
.Lmy_lsync_8:
	s_mov_b64 s[2:3], exec
	v_mbcnt_lo_u32_b32 v1, s2, 0
	v_mbcnt_hi_u32_b32 v1, s3, v1
	v_cmp_eq_u32_e32 vcc, 0, v1
	s_waitcnt vmcnt(0)
	s_and_saveexec_b64 s[6:7], vcc
	s_cbranch_execz .LBB0_3875
	s_bcnt1_i32_b64 s2, s[2:3]
	v_mov_b32_e32 v1, s2
	global_atomic_add v241, v1, s[4:5] offset:1024
